# regenerated MLA loop body + raised wave priority around the two MFMA-only clusters (QK of group 0, P*V of group 1)
# baseline (speedup 1.0000x reference)
.LBB0_559:
	s_and_b32 s5, s4, 0x80
	v_or_b32_e32 v201, s5, v125
	v_mad_u32_u24 v201, v201, s12, v0
	v_or_b32_e32 v200, s5, v132
	v_mul_u32_u24_e32 v200, 0x48, v200
	v_lshl_add_u32 v200, v200, 1, v130
	ds_read_b128 v[164:167], v201 offset:0
	ds_read_b128 v[176:179], v201 offset:3328
	ds_read_b128 v[232:235], v201 offset:6656
	ds_read_b128 v[244:247], v201 offset:9984
	ds_read_b128 v[168:171], v201 offset:64
	ds_read_b128 v[180:183], v201 offset:3392
	ds_read_b128 v[236:239], v201 offset:6720
	ds_read_b128 v[142:145], v201 offset:10048
	ds_read_b128 v[172:175], v201 offset:128
	ds_read_b128 v[184:187], v201 offset:3456
	ds_read_b128 v[240:243], v201 offset:6784
	ds_read_b128 v[146:149], v201 offset:10112
	s_setprio 1
	s_waitcnt lgkmcnt(11)
	v_mfma_f32_16x16x32_bf16 v[78:81], v[164:167], v[2:5], 0
	s_waitcnt lgkmcnt(10)
	v_mfma_f32_16x16x32_bf16 v[82:85], v[176:179], v[2:5], 0
	s_waitcnt lgkmcnt(9)
	v_mfma_f32_16x16x32_bf16 v[86:89], v[232:235], v[2:5], 0
	s_waitcnt lgkmcnt(8)
	v_mfma_f32_16x16x32_bf16 v[90:93], v[244:247], v[2:5], 0
	s_waitcnt lgkmcnt(7)
	v_mfma_f32_16x16x32_bf16 v[78:81], v[168:171], v[6:9], v[78:81]
	s_waitcnt lgkmcnt(6)
	v_mfma_f32_16x16x32_bf16 v[82:85], v[180:183], v[6:9], v[82:85]
	s_waitcnt lgkmcnt(5)
	v_mfma_f32_16x16x32_bf16 v[86:89], v[236:239], v[6:9], v[86:89]
	s_waitcnt lgkmcnt(4)
	v_mfma_f32_16x16x32_bf16 v[90:93], v[142:145], v[6:9], v[90:93]
	s_waitcnt lgkmcnt(3)
	v_mfma_f32_16x16x32_bf16 v[78:81], v[172:175], v[38:41], v[78:81]
	s_waitcnt lgkmcnt(2)
	v_mfma_f32_16x16x32_bf16 v[82:85], v[184:187], v[38:41], v[82:85]
	s_waitcnt lgkmcnt(1)
	v_mfma_f32_16x16x32_bf16 v[86:89], v[240:243], v[38:41], v[86:89]
	s_waitcnt lgkmcnt(0)
	v_mfma_f32_16x16x32_bf16 v[90:93], v[146:149], v[38:41], v[90:93]
	s_setprio 0
	v_mfma_f32_16x16x32_bf16 v[94:97], v[164:167], v[26:29], 0
	v_max3_f32 v150, v78, s18, v79
	v_max3_f32 v150, v150, v80, v81
	v_max3_f32 v150, v150, v82, v83
	v_max3_f32 v150, v150, v84, v85
	v_max3_f32 v150, v150, v86, v87
	v_max3_f32 v150, v150, v88, v89
	v_max3_f32 v150, v150, v90, v91
	v_mfma_f32_16x16x32_bf16 v[98:101], v[176:179], v[26:29], 0
	v_max3_f32 v150, v150, v92, v93
	v_mul_f32_e32 v150, 0x3e16c740, v150
	v_mov_b32_e32 v152, v150
	s_nop 1
	v_permlane16_swap_b32_e32 v152, v150
	v_max_f32_e32 v150, v150, v152
	v_mov_b32_e32 v152, v150
	s_nop 1
	v_permlane32_swap_b32_e32 v152, v150
	v_mfma_f32_16x16x32_bf16 v[102:105], v[232:235], v[26:29], 0
	v_max_f32_e32 v150, v150, v152
	v_add_f32_e32 v154, 0x41000000, v139
	v_cmp_gt_f32_e32 vcc, v150, v154
	s_cbranch_vccz .Lmla_s0_keep0
	v_max_f32_e32 v158, v139, v150
	v_sub_f32_e32 v154, v139, v158
	v_exp_f32_e32 v154, v154
	v_mov_b32_e32 v139, v158
	v_mul_f32_e32 v141, v141, v154
	v_pk_mul_f32 v[74:75], v[74:75], v[154:155] op_sel_hi:[1,0]
	v_pk_mul_f32 v[76:77], v[76:77], v[154:155] op_sel_hi:[1,0]
	v_pk_mul_f32 v[70:71], v[70:71], v[154:155] op_sel_hi:[1,0]
	v_pk_mul_f32 v[72:73], v[72:73], v[154:155] op_sel_hi:[1,0]
	v_pk_mul_f32 v[66:67], v[66:67], v[154:155] op_sel_hi:[1,0]
	v_pk_mul_f32 v[68:69], v[68:69], v[154:155] op_sel_hi:[1,0]
	v_pk_mul_f32 v[62:63], v[62:63], v[154:155] op_sel_hi:[1,0]
	v_pk_mul_f32 v[64:65], v[64:65], v[154:155] op_sel_hi:[1,0]

.Lmla_s0_keep1:
	v_fma_f32 v94, v94, s21, -v138
	v_fma_f32 v95, v95, s21, -v138
	v_exp_f32_e32 v94, v94
	v_fma_f32 v96, v96, s21, -v138
	v_exp_f32_e32 v95, v95
	v_fma_f32 v97, v97, s21, -v138
	v_exp_f32_e32 v96, v96
	s_waitcnt lgkmcnt(12)
	v_mfma_f32_16x16x32_bf16 v[70:73], v[168:171], v[78:81], v[70:73]
	v_exp_f32_e32 v97, v97
	v_fma_f32 v98, v98, s21, -v138
	v_fma_f32 v99, v99, s21, -v138
	v_exp_f32_e32 v98, v98
	v_fma_f32 v100, v100, s21, -v138
	v_exp_f32_e32 v99, v99
	v_fma_f32 v101, v101, s21, -v138
	v_exp_f32_e32 v100, v100
	s_waitcnt lgkmcnt(10)
	v_mfma_f32_16x16x32_bf16 v[74:77], v[172:175], v[82:85], v[74:77]
	v_exp_f32_e32 v101, v101
	v_add_f32_e32 v161, 0, v94
	v_add_f32_e32 v161, v95, v161
	v_add_f32_e32 v161, v96, v161
	v_add_f32_e32 v161, v97, v161
	v_cvt_pk_bf16_f32 v94, v94, v95
	v_cvt_pk_bf16_f32 v95, v96, v97
	v_fma_f32 v102, v102, s21, -v138
	s_waitcnt lgkmcnt(8)
	v_mfma_f32_16x16x32_bf16 v[70:73], v[176:179], v[82:85], v[70:73]
	v_fma_f32 v103, v103, s21, -v138
	v_exp_f32_e32 v102, v102
	v_fma_f32 v104, v104, s21, -v138
	v_exp_f32_e32 v103, v103
	v_fma_f32 v105, v105, s21, -v138
	v_exp_f32_e32 v104, v104
	v_exp_f32_e32 v105, v105
	v_add_f32_e32 v161, v98, v161
	s_waitcnt lgkmcnt(6)
	v_mfma_f32_16x16x32_bf16 v[66:69], v[232:235], v[78:81], v[66:69]
	v_add_f32_e32 v161, v99, v161
	v_add_f32_e32 v161, v100, v161
	v_add_f32_e32 v161, v101, v161
	v_cvt_pk_bf16_f32 v96, v98, v99
	v_cvt_pk_bf16_f32 v97, v100, v101
	v_fma_f32 v106, v106, s21, -v138
	v_fma_f32 v107, v107, s21, -v138
	v_exp_f32_e32 v106, v106
	s_waitcnt lgkmcnt(4)
	v_mfma_f32_16x16x32_bf16 v[62:65], v[236:239], v[78:81], v[62:65]
	v_fma_f32 v108, v108, s21, -v138
	v_exp_f32_e32 v107, v107
	v_fma_f32 v109, v109, s21, -v138
	v_exp_f32_e32 v108, v108
	v_exp_f32_e32 v109, v109
	v_add_f32_e32 v161, v102, v161
	v_add_f32_e32 v161, v103, v161
	v_add_f32_e32 v161, v104, v161
	s_waitcnt lgkmcnt(2)
	v_mfma_f32_16x16x32_bf16 v[66:69], v[240:243], v[82:85], v[66:69]
	v_add_f32_e32 v161, v105, v161
	v_cvt_pk_bf16_f32 v98, v102, v103
	v_cvt_pk_bf16_f32 v99, v104, v105
	v_add_f32_e32 v161, v106, v161
	v_add_f32_e32 v161, v107, v161
	v_add_f32_e32 v161, v108, v161
	v_add_f32_e32 v161, v109, v161
	v_cvt_pk_bf16_f32 v100, v106, v107
	s_waitcnt lgkmcnt(0)
	v_mfma_f32_16x16x32_bf16 v[62:65], v[244:247], v[82:85], v[62:65]
	v_cvt_pk_bf16_f32 v101, v108, v109
	v_add_f32_e32 v140, v140, v161
	s_setprio 1
	v_mfma_f32_16x16x32_bf16 v[58:61], v[164:167], v[94:97], v[58:61]
	v_mfma_f32_16x16x32_bf16 v[54:57], v[168:171], v[94:97], v[54:57]
	v_mfma_f32_16x16x32_bf16 v[58:61], v[172:175], v[98:101], v[58:61]
	v_mfma_f32_16x16x32_bf16 v[54:57], v[176:179], v[98:101], v[54:57]
	v_mfma_f32_16x16x32_bf16 v[50:53], v[232:235], v[94:97], v[50:53]
	v_mfma_f32_16x16x32_bf16 v[46:49], v[236:239], v[94:97], v[46:49]
	v_mfma_f32_16x16x32_bf16 v[50:53], v[240:243], v[98:101], v[50:53]
	v_mfma_f32_16x16x32_bf16 v[46:49], v[244:247], v[98:101], v[46:49]
	s_setprio 0
	v_add_u32_e32 v200, 0x2400, v200
	ds_read_b128 v[164:167], v201 offset:13312
	ds_read_b128 v[176:179], v201 offset:16640
	ds_read_b128 v[232:235], v201 offset:19968
	ds_read_b128 v[244:247], v201 offset:23296
	ds_read_b128 v[168:171], v201 offset:13376
	ds_read_b128 v[180:183], v201 offset:16704
	ds_read_b128 v[236:239], v201 offset:20032
	ds_read_b128 v[142:145], v201 offset:23360
	ds_read_b128 v[172:175], v201 offset:13440
	ds_read_b128 v[184:187], v201 offset:16768
	ds_read_b128 v[240:243], v201 offset:20096
	ds_read_b128 v[146:149], v201 offset:23424
	s_setprio 1
	s_waitcnt lgkmcnt(11)
	v_mfma_f32_16x16x32_bf16 v[78:81], v[164:167], v[2:5], 0
	s_waitcnt lgkmcnt(10)
	v_mfma_f32_16x16x32_bf16 v[82:85], v[176:179], v[2:5], 0
	s_waitcnt lgkmcnt(9)
	v_mfma_f32_16x16x32_bf16 v[86:89], v[232:235], v[2:5], 0
	s_waitcnt lgkmcnt(8)
	v_mfma_f32_16x16x32_bf16 v[90:93], v[244:247], v[2:5], 0
	s_waitcnt lgkmcnt(7)
	v_mfma_f32_16x16x32_bf16 v[78:81], v[168:171], v[6:9], v[78:81]
	s_waitcnt lgkmcnt(6)
	v_mfma_f32_16x16x32_bf16 v[82:85], v[180:183], v[6:9], v[82:85]
	s_waitcnt lgkmcnt(5)
	v_mfma_f32_16x16x32_bf16 v[86:89], v[236:239], v[6:9], v[86:89]
	s_waitcnt lgkmcnt(4)
	v_mfma_f32_16x16x32_bf16 v[90:93], v[142:145], v[6:9], v[90:93]
	s_waitcnt lgkmcnt(3)
	v_mfma_f32_16x16x32_bf16 v[78:81], v[172:175], v[38:41], v[78:81]
	s_waitcnt lgkmcnt(2)
	v_mfma_f32_16x16x32_bf16 v[82:85], v[184:187], v[38:41], v[82:85]
	s_waitcnt lgkmcnt(1)
	v_mfma_f32_16x16x32_bf16 v[86:89], v[240:243], v[38:41], v[86:89]
	s_waitcnt lgkmcnt(0)
	v_mfma_f32_16x16x32_bf16 v[90:93], v[146:149], v[38:41], v[90:93]
	s_setprio 0
	v_mfma_f32_16x16x32_bf16 v[94:97], v[164:167], v[26:29], 0
	v_max3_f32 v150, v78, s18, v79
	v_max3_f32 v150, v150, v80, v81
	v_max3_f32 v150, v150, v82, v83
	v_max3_f32 v150, v150, v84, v85
	v_max3_f32 v150, v150, v86, v87
	v_max3_f32 v150, v150, v88, v89
	v_max3_f32 v150, v150, v90, v91
	v_mfma_f32_16x16x32_bf16 v[98:101], v[176:179], v[26:29], 0
	v_max3_f32 v150, v150, v92, v93
	v_mul_f32_e32 v150, 0x3e16c740, v150
	v_mov_b32_e32 v152, v150
	s_nop 1
	v_permlane16_swap_b32_e32 v152, v150
	v_max_f32_e32 v150, v150, v152
	v_mov_b32_e32 v152, v150
	s_nop 1
	v_permlane32_swap_b32_e32 v152, v150
	v_mfma_f32_16x16x32_bf16 v[102:105], v[232:235], v[26:29], 0
	v_max_f32_e32 v150, v150, v152
	v_add_f32_e32 v154, 0x41000000, v139
	v_cmp_gt_f32_e32 vcc, v150, v154
	s_cbranch_vccz .Lmla_s1_keep0
	v_max_f32_e32 v158, v139, v150
	v_sub_f32_e32 v154, v139, v158
	v_exp_f32_e32 v154, v154
	v_mov_b32_e32 v139, v158
	v_mul_f32_e32 v141, v141, v154
	v_pk_mul_f32 v[74:75], v[74:75], v[154:155] op_sel_hi:[1,0]
	v_pk_mul_f32 v[76:77], v[76:77], v[154:155] op_sel_hi:[1,0]
	v_pk_mul_f32 v[70:71], v[70:71], v[154:155] op_sel_hi:[1,0]
	v_pk_mul_f32 v[72:73], v[72:73], v[154:155] op_sel_hi:[1,0]
	v_pk_mul_f32 v[66:67], v[66:67], v[154:155] op_sel_hi:[1,0]
	v_pk_mul_f32 v[68:69], v[68:69], v[154:155] op_sel_hi:[1,0]
	v_pk_mul_f32 v[62:63], v[62:63], v[154:155] op_sel_hi:[1,0]
	v_pk_mul_f32 v[64:65], v[64:65], v[154:155] op_sel_hi:[1,0]

.Lmla_s1_keep1:
	v_fma_f32 v94, v94, s21, -v138
	v_fma_f32 v95, v95, s21, -v138
	v_exp_f32_e32 v94, v94
	v_fma_f32 v96, v96, s21, -v138
	v_exp_f32_e32 v95, v95
	v_fma_f32 v97, v97, s21, -v138
	v_exp_f32_e32 v96, v96
	s_waitcnt lgkmcnt(12)
	v_mfma_f32_16x16x32_bf16 v[70:73], v[168:171], v[78:81], v[70:73]
	v_exp_f32_e32 v97, v97
	v_fma_f32 v98, v98, s21, -v138
	v_fma_f32 v99, v99, s21, -v138
	v_exp_f32_e32 v98, v98
	v_fma_f32 v100, v100, s21, -v138
	v_exp_f32_e32 v99, v99
	v_fma_f32 v101, v101, s21, -v138
	v_exp_f32_e32 v100, v100
	s_waitcnt lgkmcnt(10)
	v_mfma_f32_16x16x32_bf16 v[74:77], v[172:175], v[82:85], v[74:77]
	v_exp_f32_e32 v101, v101
	v_add_f32_e32 v161, 0, v94
	v_add_f32_e32 v161, v95, v161
	v_add_f32_e32 v161, v96, v161
	v_add_f32_e32 v161, v97, v161
	v_cvt_pk_bf16_f32 v94, v94, v95
	v_cvt_pk_bf16_f32 v95, v96, v97
	v_fma_f32 v102, v102, s21, -v138
	s_waitcnt lgkmcnt(8)
	v_mfma_f32_16x16x32_bf16 v[70:73], v[176:179], v[82:85], v[70:73]
	v_fma_f32 v103, v103, s21, -v138
	v_exp_f32_e32 v102, v102
	v_fma_f32 v104, v104, s21, -v138
	v_exp_f32_e32 v103, v103
	v_fma_f32 v105, v105, s21, -v138
	v_exp_f32_e32 v104, v104
	v_exp_f32_e32 v105, v105
	v_add_f32_e32 v161, v98, v161
	s_waitcnt lgkmcnt(6)
	v_mfma_f32_16x16x32_bf16 v[66:69], v[232:235], v[78:81], v[66:69]
	v_add_f32_e32 v161, v99, v161
	v_add_f32_e32 v161, v100, v161
	v_add_f32_e32 v161, v101, v161
	v_cvt_pk_bf16_f32 v96, v98, v99
	v_cvt_pk_bf16_f32 v97, v100, v101
	v_fma_f32 v106, v106, s21, -v138
	v_fma_f32 v107, v107, s21, -v138
	v_exp_f32_e32 v106, v106
	s_waitcnt lgkmcnt(4)
	v_mfma_f32_16x16x32_bf16 v[62:65], v[236:239], v[78:81], v[62:65]
	v_fma_f32 v108, v108, s21, -v138
	v_exp_f32_e32 v107, v107
	v_fma_f32 v109, v109, s21, -v138
	v_exp_f32_e32 v108, v108
	v_exp_f32_e32 v109, v109
	v_add_f32_e32 v161, v102, v161
	v_add_f32_e32 v161, v103, v161
	v_add_f32_e32 v161, v104, v161
	s_waitcnt lgkmcnt(2)
	v_mfma_f32_16x16x32_bf16 v[66:69], v[240:243], v[82:85], v[66:69]
	v_add_f32_e32 v161, v105, v161
	v_cvt_pk_bf16_f32 v98, v102, v103
	v_cvt_pk_bf16_f32 v99, v104, v105
	v_add_f32_e32 v161, v106, v161
	v_add_f32_e32 v161, v107, v161
	v_add_f32_e32 v161, v108, v161
	v_add_f32_e32 v161, v109, v161
	v_cvt_pk_bf16_f32 v100, v106, v107
	s_waitcnt lgkmcnt(0)
	v_mfma_f32_16x16x32_bf16 v[62:65], v[244:247], v[82:85], v[62:65]
	v_cvt_pk_bf16_f32 v101, v108, v109
	v_add_f32_e32 v140, v140, v161
	s_setprio 1
	v_mfma_f32_16x16x32_bf16 v[58:61], v[164:167], v[94:97], v[58:61]
	v_mfma_f32_16x16x32_bf16 v[54:57], v[168:171], v[94:97], v[54:57]
	v_mfma_f32_16x16x32_bf16 v[58:61], v[172:175], v[98:101], v[58:61]
	v_mfma_f32_16x16x32_bf16 v[54:57], v[176:179], v[98:101], v[54:57]
	v_mfma_f32_16x16x32_bf16 v[50:53], v[232:235], v[94:97], v[50:53]
	v_mfma_f32_16x16x32_bf16 v[46:49], v[236:239], v[94:97], v[46:49]
	v_mfma_f32_16x16x32_bf16 v[50:53], v[240:243], v[98:101], v[50:53]
	v_mfma_f32_16x16x32_bf16 v[46:49], v[244:247], v[98:101], v[46:49]
	s_setprio 0
	s_andn2_b64 vcc, exec, s[2:3]
	s_cbranch_vccnz .LBB0_556
	s_xor_b32 s5, s5, 0x80
	s_cmp_eq_u32 s5, 0
	s_cbranch_scc1 .Lmla_stage_buf0
	s_waitcnt vmcnt(4)
	ds_write_b128 v224, v[10:13] offset:26624
	s_waitcnt vmcnt(3)
	ds_write_b128 v229, v[14:17] offset:53248
	s_waitcnt vmcnt(2)
	ds_write_b128 v226, v[18:21] offset:26624
	s_waitcnt vmcnt(1)
	ds_write_b128 v230, v[22:25] offset:53248
	s_waitcnt vmcnt(0)
	ds_write_b128 v228, v[34:37] offset:26752
	s_branch .LBB0_556
